# P3 RWKV loader waves prefetch raw inputs four chunks ahead (four raw register sets) instead of two
# baseline (speedup 1.0000x reference)
; template <bool RWKV> __device__ __forceinline__ void scan_load_issue(ScanLd& L, const ScanSrc& S, int chunk, int lt) {
;     const int lw = lt >> 6, lane = lt & 63, sl = lane >> 2, col = 16 * lw + 4 * (lane & 3), s = chunk * SC_CH + sl; const size_t tok = (size_t)(S.tokbase + (S.rev ? T_SEQ - 1 - s : s));
;     L.rd = *(const u32x2*)(S.v[0] + tok * S.ld[0] + col); L.rk = *(const u32x2*)(S.v[1] + tok * S.ld[1] + col); L.rr = *(const u32x2*)(S.v[4] + tok * S.ld[4] + col); L.rv = *(const u32x2*)(S.v[5] + tok * S.ld[5] + col);
;     L.rkk = L.rk; L.rnb = L.rk;
;     if (RWKV) { L.rkk = *(const u32x2*)(S.v[2] + tok * S.ld[2] + col); L.rnb = *(const u32x2*)(S.v[3] + tok * S.ld[3] + col); }
; }
; template <bool RWKV> __device__ __forceinline__ void scan_item(LAS unsigned char* lds, const ScanSrc& S, int wid, int lane) {
;     f32x16 T[2];
; #pragma unroll
;     for (int a = 0; a < 2; ++a)
; #pragma unroll
;         for (int i = 0; i < 16; ++i) T[a][i] = 0.f;
;     const bool is_ld = (wid == 4) | (wid == 5) | (wid == 3) | (wid == 7); const bool is_prep = wid == 2;
;     const int lt = (wid == 4 ? 0 : wid == 5 ? 64 : wid == 3 ? 128 : 192) + lane;
;     ScanLd L;
;     constexpr int NCH = T_SEQ / SC_CH;
;     ...
;     const bool is_inv = wid == 6;
;     if (is_ld) { scan_load_issue<RWKV>(L, S, 0, lt); scan_load_finish<RWKV>(lds, L, lt); scan_load_issue<RWKV>(L, S, 1, lt); scan_load_finish<RWKV>(lds + SC_BUF, L, lt);
;                  scan_load_issue<RWKV>(L, S, 2, lt); scan_load_finish<RWKV>(lds + 2 * SC_BUF, L, lt); scan_load_issue<RWKV>(L, S, 3, lt); }
.LBB0_611:
	s_or_b64 exec, exec, s[72:73]
	s_lshl_b32 s72, s89, 25
	s_add_u32 s72, s56, s72
	s_addc_u32 s73, s57, 0
	s_add_u32 s72, s72, s93
	v_lshlrev_b32_e32 v74, 1, v20
	s_addc_u32 s73, s73, 0
	s_lshr_b32 s89, s81, 2
	v_lshl_add_u64 v[88:89], s[0:1], 0, v[74:75]
	s_lshl_b64 s[0:1], s[86:87], 1
	v_or_b32_e32 v0, s89, v122
	s_add_u32 s0, s72, s0
	v_lshlrev_b32_e32 v182, 1, v0
	v_mul_u32_u24_e32 v183, 0x50, v0
	v_mul_u32_u24_e32 v184, 48, v0
	v_mad_u32_u24 v185, v0, s88, s88
	v_mad_u32_u24 v186, v0, s88, v180
	v_mad_u32_u24 v187, v0, s88, v181
	v_lshlrev_b32_e32 v188, 2, v0
	v_lshl_add_u64 v[90:91], s[60:61], 0, v[74:75]
	v_lshl_add_u64 v[92:93], s[68:69], 0, v[74:75]
	v_lshl_add_u64 v[94:95], s[70:71], 0, v[74:75]
	v_lshl_add_u64 v[96:97], s[42:43], 0, v[74:75]
	v_lshl_add_u64 v[98:99], s[66:67], 0, v[74:75]
	s_addc_u32 s1, s73, s1
	v_lshlrev_b32_e32 v74, 1, v72
	s_ashr_i32 s66, s83, 31
	v_add_u32_e32 v0, s81, v73
	s_waitcnt lgkmcnt(0)
	s_barrier
	v_lshl_add_u64 v[100:101], s[0:1], 0, v[74:75]
	s_and_b64 s[0:1], s[40:41], exec
	s_movk_i32 s89, 0x200
	v_bfe_u32 v0, v0, 2, 4
	s_cselect_b32 s0, s89, 0xfffffe00
	v_or_b32_e32 v74, 64, v0
	v_sub_u32_e32 v189, 0, v0
	v_mov_b32_e32 v0, 0
	v_mul_hi_i32_i24_e32 v103, s0, v138
	v_mul_i32_i24_e32 v102, s0, v138
	v_mul_hi_i32_i24_e32 v105, s0, v139
	v_mul_i32_i24_e32 v104, s0, v139
	v_mul_hi_i32_i24_e32 v107, s0, v140
	v_mul_i32_i24_e32 v106, s0, v140
	v_mul_hi_i32_i24_e32 v109, s0, v141
	v_mul_i32_i24_e32 v108, s0, v141
	v_mul_hi_i32_i24_e32 v111, s0, v142
	v_mul_i32_i24_e32 v110, s0, v142
	v_mul_hi_i32_i24_e32 v113, s0, v143
	v_mul_i32_i24_e32 v112, s0, v143
	v_mul_hi_i32_i24_e32 v115, s0, v144
	v_mul_i32_i24_e32 v114, s0, v144
	v_mul_hi_i32_i24_e32 v117, s0, v145
	v_mul_i32_i24_e32 v116, s0, v145
	s_mov_b32 s67, 0
	s_movk_i32 s68, 0xfbf
	s_mov_b32 s69, 0
	s_mov_b32 s72, 0
	s_mov_b32 s70, 0
	v_mov_b32_e32 v1, v0
	v_mov_b32_e32 v2, v0
	v_mov_b32_e32 v3, v0
	v_mov_b32_e32 v4, v0
	v_mov_b32_e32 v5, v0
	v_mov_b32_e32 v6, v0
	v_mov_b32_e32 v7, v0
	v_mov_b32_e32 v8, v0
	v_mov_b32_e32 v9, v0
	v_mov_b32_e32 v10, v0
	v_mov_b32_e32 v11, v0
	v_mov_b32_e32 v12, v0
	v_mov_b32_e32 v13, v0
	v_mov_b32_e32 v14, v0
	v_mov_b32_e32 v15, v0
	v_mov_b32_e32 v16, v0
	v_mov_b32_e32 v17, v0
	v_mov_b32_e32 v18, v0
	v_mov_b32_e32 v19, v0
	v_mov_b32_e32 v20, v0
	v_mov_b32_e32 v21, v0
	v_mov_b32_e32 v22, v0
	v_mov_b32_e32 v23, v0
	v_mov_b32_e32 v24, v0
	v_mov_b32_e32 v25, v0
	v_mov_b32_e32 v26, v0
	v_mov_b32_e32 v27, v0
	v_mov_b32_e32 v28, v0
	v_mov_b32_e32 v29, v0
	v_mov_b32_e32 v30, v0
	v_mov_b32_e32 v31, v0
	v_and_b32_e32 v251, 3, v73
	v_and_b32_e32 v252, 48, v73
	v_add_u32_e32 v251, v251, v252
	v_add_u32_e32 v251, -4, v251
	v_and_b32_e32 v253, 16, v73
	v_cmp_ne_u32_e32 vcc, 0, v253
	v_and_b32_e32 v252, 3, v73
	v_add_u32_e32 v252, 28, v252
	v_cndmask_b32_e32 v251, v73, v251, vcc
	v_cndmask_b32_e64 v253, 0, 1.0, vcc
	v_cmp_lt_u32_e32 vcc, 31, v73
	v_lshlrev_b32_e32 v251, 2, v251
	v_lshlrev_b32_e32 v252, 2, v252
	v_cndmask_b32_e64 v245, 0, 1.0, vcc
	v_add_u32_e32 v248, v123, v182
	v_add_u32_e32 v249, v183, v127
	v_add_u32_e32 v250, v184, v127
	v_add_u32_e32 v33, 0xfbf, v189
	v_cndmask_b32_e64 v32, v33, v74, s[40:41]
	v_add_u32_e32 v32, s83, v32
	v_ashrrev_i32_e32 v33, 31, v32
	v_lshlrev_b64 v[34:35], 10, v[32:33]
	v_lshl_add_u64 v[234:235], v[88:89], 0, v[34:35]
	v_mad_i64_i32 v[236:237], s[0:1], v32, s79, v[90:91]
	v_mad_i64_i32 v[238:239], s[0:1], v32, s79, v[92:93]
	v_mad_i64_i32 v[240:241], s[0:1], v32, s79, v[94:95]
	v_lshl_add_u64 v[242:243], v[96:97], 0, v[34:35]
	v_lshl_add_u64 v[246:247], v[98:99], 0, v[34:35]
	s_and_b64 s[0:1], s[40:41], exec
	s_mov_b32 s98, 0x4000
	s_cselect_b32 s98, s98, 0xffffc000
	s_cselect_b32 s99, 0, -1
	s_mov_b32 s100, 0xc000
	s_cselect_b32 s100, s100, 0xffff4000
	s_cselect_b32 s101, 0, -1
	s_cmp_lt_i32 s3, 3
	s_cbranch_scc1 .Lrw_init_done
	s_cmp_eq_u32 s3, 6
	s_cbranch_scc1 .Lrw_init_done
	global_load_dwordx2 v[222:223], v[234:235], off
	global_load_dwordx2 v[224:225], v[236:237], off
	global_load_dwordx2 v[226:227], v[238:239], off
	global_load_dwordx2 v[228:229], v[240:241], off
	global_load_dwordx2 v[230:231], v[242:243], off
	global_load_dwordx2 v[232:233], v[246:247], off
	v_lshl_add_u64 v[234:235], v[234:235], 0, s[98:99]
	v_lshl_add_u64 v[236:237], v[236:237], 0, s[100:101]
	v_lshl_add_u64 v[238:239], v[238:239], 0, s[100:101]
	v_lshl_add_u64 v[240:241], v[240:241], 0, s[100:101]
	v_lshl_add_u64 v[242:243], v[242:243], 0, s[98:99]
	v_lshl_add_u64 v[246:247], v[246:247], 0, s[98:99]
	global_load_dwordx2 v[0:1], v[234:235], off
	global_load_dwordx2 v[2:3], v[236:237], off
	global_load_dwordx2 v[4:5], v[238:239], off
	global_load_dwordx2 v[6:7], v[240:241], off
	global_load_dwordx2 v[8:9], v[242:243], off
	global_load_dwordx2 v[10:11], v[246:247], off
	v_lshl_add_u64 v[234:235], v[234:235], 0, s[98:99]
	v_lshl_add_u64 v[236:237], v[236:237], 0, s[100:101]
	v_lshl_add_u64 v[238:239], v[238:239], 0, s[100:101]
	v_lshl_add_u64 v[240:241], v[240:241], 0, s[100:101]
	v_lshl_add_u64 v[242:243], v[242:243], 0, s[98:99]
	v_lshl_add_u64 v[246:247], v[246:247], 0, s[98:99]
	global_load_dwordx2 v[12:13], v[234:235], off
	global_load_dwordx2 v[14:15], v[236:237], off
	global_load_dwordx2 v[16:17], v[238:239], off
	global_load_dwordx2 v[18:19], v[240:241], off
	global_load_dwordx2 v[20:21], v[242:243], off
	global_load_dwordx2 v[22:23], v[246:247], off

; __device__ __forceinline__ void unpack4(const u32x2 w, float (&f)[4]) { f[0] = bflo(w.x); f[1] = bfhi(w.x); f[2] = bflo(w.y); f[3] = bfhi(w.y); }
; template <bool RWKV> __device__ __forceinline__ void scan_load_finish(LAS unsigned char* buf, const ScanLd& L, int lt) {
;     const int lw = lt >> 6, lane = lt & 63, sl = lane >> 2, col = 16 * lw + 4 * (lane & 3);
;     float d[4], c[4], k[4], r[4], v[4], kk[4], nb[4];
;     unpack4(L.rd, d); unpack4(L.rk, k); unpack4(L.rr, r); unpack4(L.rv, v); unpack4(L.rkk, kk); unpack4(L.rnb, nb);
; #pragma unroll
;     for (int i = 0; i < 4; ++i) c[i] = d[i];
; #pragma unroll
;     for (int dl = 4; dl < 64; dl <<= 1)
; #pragma unroll
;         for (int i = 0; i < 4; ++i) { const float t = __shfl_up(c[i], dl); c[i] += (lane >= dl) ? t : 0.f; }
;     float o1[4], o2[4], o3[4], o4[4]; f32x4 we;
; #pragma unroll
;     for (int i = 0; i < 4; ++i) { const float W = __expf(-c[i]), iW = __expf(c[i]), Wp = __expf(d[i] - c[i]); o1[i] = RWKV ? kk[i] * Wp : 0.f; o2[i] = RWKV ? nb[i] * iW : 0.f; o3[i] = k[i] * iW; o4[i] = r[i] * W; we[i] = W; }
;     u32x2 w;
;     w.x = cvt2(o1[0], o1[1]); w.y = cvt2(o1[2], o1[3]); *(LAS u32x2*)(buf + SB_XA + sl * 144 + col * 2) = w;
;     w.x = cvt2(o4[0], o4[1]); w.y = cvt2(o4[2], o4[3]); *(LAS u32x2*)(buf + SB_XA + (16 + sl) * 144 + col * 2) = w;
;     w.x = cvt2(o2[0], o2[1]); w.y = cvt2(o2[2], o2[3]); *(LAS u32x2*)(buf + SB_XB + sl * 144 + col * 2) = w;
;     w.x = cvt2(o3[0], o3[1]); w.y = cvt2(o3[2], o3[3]); *(LAS u32x2*)(buf + SB_XB + (16 + sl) * 144 + col * 2) = w;
; #pragma unroll
;     for (int i = 0; i < 4; ++i) {
;         *(LAS unsigned short*)(buf + SB_XBT + (col + i) * 80 + sl * 2) = (unsigned short)(cvt2(o2[i], 0.f) & 0xffffu);
;         *(LAS unsigned short*)(buf + SB_XBT + (col + i) * 80 + (16 + sl) * 2) = (unsigned short)(cvt2(o3[i], 0.f) & 0xffffu);
;         *(LAS unsigned short*)(buf + SB_VT + (col + i) * 48 + sl * 2) = (unsigned short)(cvt2(v[i], 0.f) & 0xffffu); }
; template <bool RWKV> __device__ __forceinline__ void scan_item(LAS unsigned char* lds, const ScanSrc& S, int wid, int lane) {
;     ...
;             if (c + 3 < NCH) scan_load_finish<RWKV>(lds + ((b0 + 3) & 3) * SC_BUF, L, lt);
;             if (c + 4 < NCH) scan_load_issue<RWKV>(L, S, c + 4, lt); }
.LBB0_640:
	s_cmpk_gt_u32 s69, 0xfc
	s_cbranch_scc1 .LBB0_613
	s_add_i32 s0, s70, -1
	s_and_b32 s0, s0, 3
	s_mulk_i32 s0, 0x4500
	v_add_u32_e32 v190, s0, v250
	s_and_b32 s1, s69, 3
	s_cmp_eq_u32 s1, 1
	s_cbranch_scc1 .Lrw_ld_s1
	s_cmp_eq_u32 s1, 2
	s_cbranch_scc1 .Lrw_ld_s2
	s_cmp_eq_u32 s1, 3
	s_cbranch_scc1 .Lrw_ld_s3
	s_cmpk_gt_u32 s69, 0xf8
	s_cbranch_scc1 .Lrw_ld_s0_tail
	s_waitcnt vmcnt(18)
	v_lshlrev_b32_e32 v32, 16, v76
	v_and_b32_e32 v33, 0xffff0000, v76
	v_lshlrev_b32_e32 v34, 16, v77
	v_and_b32_e32 v35, 0xffff0000, v77
	v_mul_f32_e32 v52, 0x3fb8aa3b, v32
	v_mul_f32_e32 v53, 0x3fb8aa3b, v33
	v_mul_f32_e32 v54, 0x3fb8aa3b, v34
	v_mul_f32_e32 v55, 0x3fb8aa3b, v35
	v_add_f32_dpp v52, v52, v52 row_shr:4 row_mask:0xf bank_mask:0xf
	v_add_f32_dpp v53, v53, v53 row_shr:4 row_mask:0xf bank_mask:0xf
	v_add_f32_dpp v54, v54, v54 row_shr:4 row_mask:0xf bank_mask:0xf
	v_add_f32_dpp v55, v55, v55 row_shr:4 row_mask:0xf bank_mask:0xf
	v_add_f32_dpp v52, v52, v52 row_shr:8 row_mask:0xf bank_mask:0xf
	v_add_f32_dpp v53, v53, v53 row_shr:8 row_mask:0xf bank_mask:0xf
	v_add_f32_dpp v54, v54, v54 row_shr:8 row_mask:0xf bank_mask:0xf
	v_add_f32_dpp v55, v55, v55 row_shr:8 row_mask:0xf bank_mask:0xf
	ds_bpermute_b32 v60, v251, v52
	ds_bpermute_b32 v61, v251, v53
	ds_bpermute_b32 v62, v251, v54
	ds_bpermute_b32 v63, v251, v55
	ds_write_b16 v190, v82 offset:14336
	ds_write_b16_d16_hi v190, v82 offset:14384
	ds_write_b16 v190, v83 offset:14432
	ds_write_b16_d16_hi v190, v83 offset:14480
	v_lshlrev_b32_e32 v36, 16, v78
	v_and_b32_e32 v37, 0xffff0000, v78
	v_lshlrev_b32_e32 v38, 16, v79
	v_and_b32_e32 v39, 0xffff0000, v79
	v_lshlrev_b32_e32 v40, 16, v80
	v_and_b32_e32 v41, 0xffff0000, v80
	v_lshlrev_b32_e32 v42, 16, v81
	v_and_b32_e32 v43, 0xffff0000, v81
	v_lshlrev_b32_e32 v44, 16, v84
	v_and_b32_e32 v45, 0xffff0000, v84
	v_lshlrev_b32_e32 v46, 16, v85
	v_and_b32_e32 v47, 0xffff0000, v85
	v_lshlrev_b32_e32 v48, 16, v86
	v_and_b32_e32 v49, 0xffff0000, v86
	v_lshlrev_b32_e32 v50, 16, v87
	v_and_b32_e32 v51, 0xffff0000, v87
	s_waitcnt lgkmcnt(4)
	v_fmac_f32_e32 v52, v60, v253
	v_fmac_f32_e32 v53, v61, v253
	v_fmac_f32_e32 v54, v62, v253
	v_fmac_f32_e32 v55, v63, v253
	ds_bpermute_b32 v60, v252, v52
	ds_bpermute_b32 v61, v252, v53
	ds_bpermute_b32 v62, v252, v54
	ds_bpermute_b32 v63, v252, v55
	global_load_dwordx2 v[76:77], v[234:235], off
	global_load_dwordx2 v[78:79], v[236:237], off
	global_load_dwordx2 v[80:81], v[238:239], off
	global_load_dwordx2 v[82:83], v[240:241], off
	global_load_dwordx2 v[84:85], v[242:243], off
	global_load_dwordx2 v[86:87], v[246:247], off
	v_lshl_add_u64 v[234:235], v[234:235], 0, s[98:99]
	v_lshl_add_u64 v[236:237], v[236:237], 0, s[100:101]
	v_lshl_add_u64 v[238:239], v[238:239], 0, s[100:101]
	v_lshl_add_u64 v[240:241], v[240:241], 0, s[100:101]
	v_lshl_add_u64 v[242:243], v[242:243], 0, s[98:99]
	v_lshl_add_u64 v[246:247], v[246:247], 0, s[98:99]
	s_waitcnt lgkmcnt(0)
	v_fmac_f32_e32 v52, v60, v245
	v_fmac_f32_e32 v53, v61, v245
	v_fmac_f32_e32 v54, v62, v245
	v_fmac_f32_e32 v55, v63, v245
	s_branch .Lrw_ldfin

; __device__ __forceinline__ void unpack4(const u32x2 w, float (&f)[4]) { f[0] = bflo(w.x); f[1] = bfhi(w.x); f[2] = bflo(w.y); f[3] = bfhi(w.y); }
; template <bool RWKV> __device__ __forceinline__ void scan_load_finish(LAS unsigned char* buf, const ScanLd& L, int lt) {
;     const int lw = lt >> 6, lane = lt & 63, sl = lane >> 2, col = 16 * lw + 4 * (lane & 3);
;     float d[4], c[4], k[4], r[4], v[4], kk[4], nb[4];
;     unpack4(L.rd, d); unpack4(L.rk, k); unpack4(L.rr, r); unpack4(L.rv, v); unpack4(L.rkk, kk); unpack4(L.rnb, nb);
; #pragma unroll
;     for (int i = 0; i < 4; ++i) c[i] = d[i];
; #pragma unroll
;     for (int dl = 4; dl < 64; dl <<= 1)
; #pragma unroll
;         for (int i = 0; i < 4; ++i) { const float t = __shfl_up(c[i], dl); c[i] += (lane >= dl) ? t : 0.f; }
;     float o1[4], o2[4], o3[4], o4[4]; f32x4 we;
; #pragma unroll
;     for (int i = 0; i < 4; ++i) { const float W = __expf(-c[i]), iW = __expf(c[i]), Wp = __expf(d[i] - c[i]); o1[i] = RWKV ? kk[i] * Wp : 0.f; o2[i] = RWKV ? nb[i] * iW : 0.f; o3[i] = k[i] * iW; o4[i] = r[i] * W; we[i] = W; }
;     u32x2 w;
;     w.x = cvt2(o1[0], o1[1]); w.y = cvt2(o1[2], o1[3]); *(LAS u32x2*)(buf + SB_XA + sl * 144 + col * 2) = w;
;     w.x = cvt2(o4[0], o4[1]); w.y = cvt2(o4[2], o4[3]); *(LAS u32x2*)(buf + SB_XA + (16 + sl) * 144 + col * 2) = w;
;     w.x = cvt2(o2[0], o2[1]); w.y = cvt2(o2[2], o2[3]); *(LAS u32x2*)(buf + SB_XB + sl * 144 + col * 2) = w;
;     w.x = cvt2(o3[0], o3[1]); w.y = cvt2(o3[2], o3[3]); *(LAS u32x2*)(buf + SB_XB + (16 + sl) * 144 + col * 2) = w;
; #pragma unroll
;     for (int i = 0; i < 4; ++i) {
;         *(LAS unsigned short*)(buf + SB_XBT + (col + i) * 80 + sl * 2) = (unsigned short)(cvt2(o2[i], 0.f) & 0xffffu);
;         *(LAS unsigned short*)(buf + SB_XBT + (col + i) * 80 + (16 + sl) * 2) = (unsigned short)(cvt2(o3[i], 0.f) & 0xffffu);
;         *(LAS unsigned short*)(buf + SB_VT + (col + i) * 48 + sl * 2) = (unsigned short)(cvt2(v[i], 0.f) & 0xffffu); }
; template <bool RWKV> __device__ __forceinline__ void scan_item(LAS unsigned char* lds, const ScanSrc& S, int wid, int lane) {
;     ...
;             if (c + 3 < NCH) scan_load_finish<RWKV>(lds + ((b0 + 3) & 3) * SC_BUF, L, lt);
;             if (c + 4 < NCH) scan_load_issue<RWKV>(L, S, c + 4, lt); }
.Lrw_ld_s1:
	s_cmpk_gt_u32 s69, 0xf8
	s_cbranch_scc1 .Lrw_ld_s1_tail
	s_waitcnt vmcnt(18)
	v_lshlrev_b32_e32 v32, 16, v222
	v_and_b32_e32 v33, 0xffff0000, v222
	v_lshlrev_b32_e32 v34, 16, v223
	v_and_b32_e32 v35, 0xffff0000, v223
	v_mul_f32_e32 v52, 0x3fb8aa3b, v32
	v_mul_f32_e32 v53, 0x3fb8aa3b, v33
	v_mul_f32_e32 v54, 0x3fb8aa3b, v34
	v_mul_f32_e32 v55, 0x3fb8aa3b, v35
	v_add_f32_dpp v52, v52, v52 row_shr:4 row_mask:0xf bank_mask:0xf
	v_add_f32_dpp v53, v53, v53 row_shr:4 row_mask:0xf bank_mask:0xf
	v_add_f32_dpp v54, v54, v54 row_shr:4 row_mask:0xf bank_mask:0xf
	v_add_f32_dpp v55, v55, v55 row_shr:4 row_mask:0xf bank_mask:0xf
	v_add_f32_dpp v52, v52, v52 row_shr:8 row_mask:0xf bank_mask:0xf
	v_add_f32_dpp v53, v53, v53 row_shr:8 row_mask:0xf bank_mask:0xf
	v_add_f32_dpp v54, v54, v54 row_shr:8 row_mask:0xf bank_mask:0xf
	v_add_f32_dpp v55, v55, v55 row_shr:8 row_mask:0xf bank_mask:0xf
	ds_bpermute_b32 v60, v251, v52
	ds_bpermute_b32 v61, v251, v53
	ds_bpermute_b32 v62, v251, v54
	ds_bpermute_b32 v63, v251, v55
	ds_write_b16 v190, v228 offset:14336
	ds_write_b16_d16_hi v190, v228 offset:14384
	ds_write_b16 v190, v229 offset:14432
	ds_write_b16_d16_hi v190, v229 offset:14480
	v_lshlrev_b32_e32 v36, 16, v224
	v_and_b32_e32 v37, 0xffff0000, v224
	v_lshlrev_b32_e32 v38, 16, v225
	v_and_b32_e32 v39, 0xffff0000, v225
	v_lshlrev_b32_e32 v40, 16, v226
	v_and_b32_e32 v41, 0xffff0000, v226
	v_lshlrev_b32_e32 v42, 16, v227
	v_and_b32_e32 v43, 0xffff0000, v227
	v_lshlrev_b32_e32 v44, 16, v230
	v_and_b32_e32 v45, 0xffff0000, v230
	v_lshlrev_b32_e32 v46, 16, v231
	v_and_b32_e32 v47, 0xffff0000, v231
	v_lshlrev_b32_e32 v48, 16, v232
	v_and_b32_e32 v49, 0xffff0000, v232
	v_lshlrev_b32_e32 v50, 16, v233
	v_and_b32_e32 v51, 0xffff0000, v233
	s_waitcnt lgkmcnt(4)
	v_fmac_f32_e32 v52, v60, v253
	v_fmac_f32_e32 v53, v61, v253
	v_fmac_f32_e32 v54, v62, v253
	v_fmac_f32_e32 v55, v63, v253
	ds_bpermute_b32 v60, v252, v52
	ds_bpermute_b32 v61, v252, v53
	ds_bpermute_b32 v62, v252, v54
	ds_bpermute_b32 v63, v252, v55
	global_load_dwordx2 v[222:223], v[234:235], off
	global_load_dwordx2 v[224:225], v[236:237], off
	global_load_dwordx2 v[226:227], v[238:239], off
	global_load_dwordx2 v[228:229], v[240:241], off
	global_load_dwordx2 v[230:231], v[242:243], off
	global_load_dwordx2 v[232:233], v[246:247], off
	v_lshl_add_u64 v[234:235], v[234:235], 0, s[98:99]
	v_lshl_add_u64 v[236:237], v[236:237], 0, s[100:101]
	v_lshl_add_u64 v[238:239], v[238:239], 0, s[100:101]
	v_lshl_add_u64 v[240:241], v[240:241], 0, s[100:101]
	v_lshl_add_u64 v[242:243], v[242:243], 0, s[98:99]
	v_lshl_add_u64 v[246:247], v[246:247], 0, s[98:99]
	s_waitcnt lgkmcnt(0)
	v_fmac_f32_e32 v52, v60, v245
	v_fmac_f32_e32 v53, v61, v245
	v_fmac_f32_e32 v54, v62, v245
	v_fmac_f32_e32 v55, v63, v245
	s_branch .Lrw_ldfin
.Lrw_ld_s1_tail:
	s_waitcnt vmcnt(0)
	v_lshlrev_b32_e32 v32, 16, v222
	v_and_b32_e32 v33, 0xffff0000, v222
	v_lshlrev_b32_e32 v34, 16, v223
	v_and_b32_e32 v35, 0xffff0000, v223
	v_mul_f32_e32 v52, 0x3fb8aa3b, v32
	v_mul_f32_e32 v53, 0x3fb8aa3b, v33
	v_mul_f32_e32 v54, 0x3fb8aa3b, v34
	v_mul_f32_e32 v55, 0x3fb8aa3b, v35
	v_add_f32_dpp v52, v52, v52 row_shr:4 row_mask:0xf bank_mask:0xf
	v_add_f32_dpp v53, v53, v53 row_shr:4 row_mask:0xf bank_mask:0xf
	v_add_f32_dpp v54, v54, v54 row_shr:4 row_mask:0xf bank_mask:0xf
	v_add_f32_dpp v55, v55, v55 row_shr:4 row_mask:0xf bank_mask:0xf
	v_add_f32_dpp v52, v52, v52 row_shr:8 row_mask:0xf bank_mask:0xf
	v_add_f32_dpp v53, v53, v53 row_shr:8 row_mask:0xf bank_mask:0xf
	v_add_f32_dpp v54, v54, v54 row_shr:8 row_mask:0xf bank_mask:0xf
	v_add_f32_dpp v55, v55, v55 row_shr:8 row_mask:0xf bank_mask:0xf
	ds_bpermute_b32 v60, v251, v52
	ds_bpermute_b32 v61, v251, v53
	ds_bpermute_b32 v62, v251, v54
	ds_bpermute_b32 v63, v251, v55
	ds_write_b16 v190, v228 offset:14336
	ds_write_b16_d16_hi v190, v228 offset:14384
	ds_write_b16 v190, v229 offset:14432
	ds_write_b16_d16_hi v190, v229 offset:14480
	v_lshlrev_b32_e32 v36, 16, v224
	v_and_b32_e32 v37, 0xffff0000, v224
	v_lshlrev_b32_e32 v38, 16, v225
	v_and_b32_e32 v39, 0xffff0000, v225
	v_lshlrev_b32_e32 v40, 16, v226
	v_and_b32_e32 v41, 0xffff0000, v226
	v_lshlrev_b32_e32 v42, 16, v227
	v_and_b32_e32 v43, 0xffff0000, v227
	v_lshlrev_b32_e32 v44, 16, v230
	v_and_b32_e32 v45, 0xffff0000, v230
	v_lshlrev_b32_e32 v46, 16, v231
	v_and_b32_e32 v47, 0xffff0000, v231
	v_lshlrev_b32_e32 v48, 16, v232
	v_and_b32_e32 v49, 0xffff0000, v232
	v_lshlrev_b32_e32 v50, 16, v233
	v_and_b32_e32 v51, 0xffff0000, v233
	s_waitcnt lgkmcnt(4)
	v_fmac_f32_e32 v52, v60, v253
	v_fmac_f32_e32 v53, v61, v253
	v_fmac_f32_e32 v54, v62, v253
	v_fmac_f32_e32 v55, v63, v253
	ds_bpermute_b32 v60, v252, v52
	ds_bpermute_b32 v61, v252, v53
	ds_bpermute_b32 v62, v252, v54
	ds_bpermute_b32 v63, v252, v55
	s_waitcnt lgkmcnt(0)
	v_fmac_f32_e32 v52, v60, v245
	v_fmac_f32_e32 v53, v61, v245
	v_fmac_f32_e32 v54, v62, v245
	v_fmac_f32_e32 v55, v63, v245
	s_branch .Lrw_ldfin
; __device__ __forceinline__ void unpack4(const u32x2 w, float (&f)[4]) { f[0] = bflo(w.x); f[1] = bfhi(w.x); f[2] = bflo(w.y); f[3] = bfhi(w.y); }
; template <bool RWKV> __device__ __forceinline__ void scan_load_finish(LAS unsigned char* buf, const ScanLd& L, int lt) {
;     const int lw = lt >> 6, lane = lt & 63, sl = lane >> 2, col = 16 * lw + 4 * (lane & 3);
;     float d[4], c[4], k[4], r[4], v[4], kk[4], nb[4];
;     unpack4(L.rd, d); unpack4(L.rk, k); unpack4(L.rr, r); unpack4(L.rv, v); unpack4(L.rkk, kk); unpack4(L.rnb, nb);
; #pragma unroll
;     for (int i = 0; i < 4; ++i) c[i] = d[i];
; #pragma unroll
;     for (int dl = 4; dl < 64; dl <<= 1)
; #pragma unroll
;         for (int i = 0; i < 4; ++i) { const float t = __shfl_up(c[i], dl); c[i] += (lane >= dl) ? t : 0.f; }
;     float o1[4], o2[4], o3[4], o4[4]; f32x4 we;
; #pragma unroll
;     for (int i = 0; i < 4; ++i) { const float W = __expf(-c[i]), iW = __expf(c[i]), Wp = __expf(d[i] - c[i]); o1[i] = RWKV ? kk[i] * Wp : 0.f; o2[i] = RWKV ? nb[i] * iW : 0.f; o3[i] = k[i] * iW; o4[i] = r[i] * W; we[i] = W; }
;     u32x2 w;
;     w.x = cvt2(o1[0], o1[1]); w.y = cvt2(o1[2], o1[3]); *(LAS u32x2*)(buf + SB_XA + sl * 144 + col * 2) = w;
;     w.x = cvt2(o4[0], o4[1]); w.y = cvt2(o4[2], o4[3]); *(LAS u32x2*)(buf + SB_XA + (16 + sl) * 144 + col * 2) = w;
;     w.x = cvt2(o2[0], o2[1]); w.y = cvt2(o2[2], o2[3]); *(LAS u32x2*)(buf + SB_XB + sl * 144 + col * 2) = w;
;     w.x = cvt2(o3[0], o3[1]); w.y = cvt2(o3[2], o3[3]); *(LAS u32x2*)(buf + SB_XB + (16 + sl) * 144 + col * 2) = w;
; #pragma unroll
;     for (int i = 0; i < 4; ++i) {
;         *(LAS unsigned short*)(buf + SB_XBT + (col + i) * 80 + sl * 2) = (unsigned short)(cvt2(o2[i], 0.f) & 0xffffu);
;         *(LAS unsigned short*)(buf + SB_XBT + (col + i) * 80 + (16 + sl) * 2) = (unsigned short)(cvt2(o3[i], 0.f) & 0xffffu);
;         *(LAS unsigned short*)(buf + SB_VT + (col + i) * 48 + sl * 2) = (unsigned short)(cvt2(v[i], 0.f) & 0xffffu); }
; template <bool RWKV> __device__ __forceinline__ void scan_item(LAS unsigned char* lds, const ScanSrc& S, int wid, int lane) {
;     ...
;             if (c + 3 < NCH) scan_load_finish<RWKV>(lds + ((b0 + 3) & 3) * SC_BUF, L, lt);
;             if (c + 4 < NCH) scan_load_issue<RWKV>(L, S, c + 4, lt); }
.Lrw_ld_s2:
	s_cmpk_gt_u32 s69, 0xf8
	s_cbranch_scc1 .Lrw_ld_s2_tail
	s_waitcnt vmcnt(18)
	v_lshlrev_b32_e32 v32, 16, v0
	v_and_b32_e32 v33, 0xffff0000, v0
	v_lshlrev_b32_e32 v34, 16, v1
	v_and_b32_e32 v35, 0xffff0000, v1
	v_mul_f32_e32 v52, 0x3fb8aa3b, v32
	v_mul_f32_e32 v53, 0x3fb8aa3b, v33
	v_mul_f32_e32 v54, 0x3fb8aa3b, v34
	v_mul_f32_e32 v55, 0x3fb8aa3b, v35
	v_add_f32_dpp v52, v52, v52 row_shr:4 row_mask:0xf bank_mask:0xf
	v_add_f32_dpp v53, v53, v53 row_shr:4 row_mask:0xf bank_mask:0xf
	v_add_f32_dpp v54, v54, v54 row_shr:4 row_mask:0xf bank_mask:0xf
	v_add_f32_dpp v55, v55, v55 row_shr:4 row_mask:0xf bank_mask:0xf
	v_add_f32_dpp v52, v52, v52 row_shr:8 row_mask:0xf bank_mask:0xf
	v_add_f32_dpp v53, v53, v53 row_shr:8 row_mask:0xf bank_mask:0xf
	v_add_f32_dpp v54, v54, v54 row_shr:8 row_mask:0xf bank_mask:0xf
	v_add_f32_dpp v55, v55, v55 row_shr:8 row_mask:0xf bank_mask:0xf
	ds_bpermute_b32 v60, v251, v52
	ds_bpermute_b32 v61, v251, v53
	ds_bpermute_b32 v62, v251, v54
	ds_bpermute_b32 v63, v251, v55
	ds_write_b16 v190, v6 offset:14336
	ds_write_b16_d16_hi v190, v6 offset:14384
	ds_write_b16 v190, v7 offset:14432
	ds_write_b16_d16_hi v190, v7 offset:14480
	v_lshlrev_b32_e32 v36, 16, v2
	v_and_b32_e32 v37, 0xffff0000, v2
	v_lshlrev_b32_e32 v38, 16, v3
	v_and_b32_e32 v39, 0xffff0000, v3
	v_lshlrev_b32_e32 v40, 16, v4
	v_and_b32_e32 v41, 0xffff0000, v4
	v_lshlrev_b32_e32 v42, 16, v5
	v_and_b32_e32 v43, 0xffff0000, v5
	v_lshlrev_b32_e32 v44, 16, v8
	v_and_b32_e32 v45, 0xffff0000, v8
	v_lshlrev_b32_e32 v46, 16, v9
	v_and_b32_e32 v47, 0xffff0000, v9
	v_lshlrev_b32_e32 v48, 16, v10
	v_and_b32_e32 v49, 0xffff0000, v10
	v_lshlrev_b32_e32 v50, 16, v11
	v_and_b32_e32 v51, 0xffff0000, v11
	s_waitcnt lgkmcnt(4)
	v_fmac_f32_e32 v52, v60, v253
	v_fmac_f32_e32 v53, v61, v253
	v_fmac_f32_e32 v54, v62, v253
	v_fmac_f32_e32 v55, v63, v253
	ds_bpermute_b32 v60, v252, v52
	ds_bpermute_b32 v61, v252, v53
	ds_bpermute_b32 v62, v252, v54
	ds_bpermute_b32 v63, v252, v55
	global_load_dwordx2 v[0:1], v[234:235], off
	global_load_dwordx2 v[2:3], v[236:237], off
	global_load_dwordx2 v[4:5], v[238:239], off
	global_load_dwordx2 v[6:7], v[240:241], off
	global_load_dwordx2 v[8:9], v[242:243], off
	global_load_dwordx2 v[10:11], v[246:247], off
	v_lshl_add_u64 v[234:235], v[234:235], 0, s[98:99]
	v_lshl_add_u64 v[236:237], v[236:237], 0, s[100:101]
	v_lshl_add_u64 v[238:239], v[238:239], 0, s[100:101]
	v_lshl_add_u64 v[240:241], v[240:241], 0, s[100:101]
	v_lshl_add_u64 v[242:243], v[242:243], 0, s[98:99]
	v_lshl_add_u64 v[246:247], v[246:247], 0, s[98:99]
	s_waitcnt lgkmcnt(0)
	v_fmac_f32_e32 v52, v60, v245
	v_fmac_f32_e32 v53, v61, v245
	v_fmac_f32_e32 v54, v62, v245
	v_fmac_f32_e32 v55, v63, v245
	s_branch .Lrw_ldfin
.Lrw_ld_s2_tail:
	s_waitcnt vmcnt(0)
	v_lshlrev_b32_e32 v32, 16, v0
	v_and_b32_e32 v33, 0xffff0000, v0
	v_lshlrev_b32_e32 v34, 16, v1
	v_and_b32_e32 v35, 0xffff0000, v1
	v_mul_f32_e32 v52, 0x3fb8aa3b, v32
	v_mul_f32_e32 v53, 0x3fb8aa3b, v33
	v_mul_f32_e32 v54, 0x3fb8aa3b, v34
	v_mul_f32_e32 v55, 0x3fb8aa3b, v35
	v_add_f32_dpp v52, v52, v52 row_shr:4 row_mask:0xf bank_mask:0xf
	v_add_f32_dpp v53, v53, v53 row_shr:4 row_mask:0xf bank_mask:0xf
	v_add_f32_dpp v54, v54, v54 row_shr:4 row_mask:0xf bank_mask:0xf
	v_add_f32_dpp v55, v55, v55 row_shr:4 row_mask:0xf bank_mask:0xf
	v_add_f32_dpp v52, v52, v52 row_shr:8 row_mask:0xf bank_mask:0xf
	v_add_f32_dpp v53, v53, v53 row_shr:8 row_mask:0xf bank_mask:0xf
	v_add_f32_dpp v54, v54, v54 row_shr:8 row_mask:0xf bank_mask:0xf
	v_add_f32_dpp v55, v55, v55 row_shr:8 row_mask:0xf bank_mask:0xf
	ds_bpermute_b32 v60, v251, v52
	ds_bpermute_b32 v61, v251, v53
	ds_bpermute_b32 v62, v251, v54
	ds_bpermute_b32 v63, v251, v55
	ds_write_b16 v190, v6 offset:14336
	ds_write_b16_d16_hi v190, v6 offset:14384
	ds_write_b16 v190, v7 offset:14432
	ds_write_b16_d16_hi v190, v7 offset:14480
	v_lshlrev_b32_e32 v36, 16, v2
	v_and_b32_e32 v37, 0xffff0000, v2
	v_lshlrev_b32_e32 v38, 16, v3
	v_and_b32_e32 v39, 0xffff0000, v3
	v_lshlrev_b32_e32 v40, 16, v4
	v_and_b32_e32 v41, 0xffff0000, v4
	v_lshlrev_b32_e32 v42, 16, v5
	v_and_b32_e32 v43, 0xffff0000, v5
	v_lshlrev_b32_e32 v44, 16, v8
	v_and_b32_e32 v45, 0xffff0000, v8
	v_lshlrev_b32_e32 v46, 16, v9
	v_and_b32_e32 v47, 0xffff0000, v9
	v_lshlrev_b32_e32 v48, 16, v10
	v_and_b32_e32 v49, 0xffff0000, v10
	v_lshlrev_b32_e32 v50, 16, v11
	v_and_b32_e32 v51, 0xffff0000, v11
	s_waitcnt lgkmcnt(4)
	v_fmac_f32_e32 v52, v60, v253
	v_fmac_f32_e32 v53, v61, v253
	v_fmac_f32_e32 v54, v62, v253
	v_fmac_f32_e32 v55, v63, v253
	ds_bpermute_b32 v60, v252, v52
	ds_bpermute_b32 v61, v252, v53
	ds_bpermute_b32 v62, v252, v54
	ds_bpermute_b32 v63, v252, v55
	s_waitcnt lgkmcnt(0)
	v_fmac_f32_e32 v52, v60, v245
	v_fmac_f32_e32 v53, v61, v245
	v_fmac_f32_e32 v54, v62, v245
	v_fmac_f32_e32 v55, v63, v245
	s_branch .Lrw_ldfin
; __device__ __forceinline__ void unpack4(const u32x2 w, float (&f)[4]) { f[0] = bflo(w.x); f[1] = bfhi(w.x); f[2] = bflo(w.y); f[3] = bfhi(w.y); }
; template <bool RWKV> __device__ __forceinline__ void scan_load_finish(LAS unsigned char* buf, const ScanLd& L, int lt) {
;     const int lw = lt >> 6, lane = lt & 63, sl = lane >> 2, col = 16 * lw + 4 * (lane & 3);
;     float d[4], c[4], k[4], r[4], v[4], kk[4], nb[4];
;     unpack4(L.rd, d); unpack4(L.rk, k); unpack4(L.rr, r); unpack4(L.rv, v); unpack4(L.rkk, kk); unpack4(L.rnb, nb);
; #pragma unroll
;     for (int i = 0; i < 4; ++i) c[i] = d[i];
; #pragma unroll
;     for (int dl = 4; dl < 64; dl <<= 1)
; #pragma unroll
;         for (int i = 0; i < 4; ++i) { const float t = __shfl_up(c[i], dl); c[i] += (lane >= dl) ? t : 0.f; }
;     float o1[4], o2[4], o3[4], o4[4]; f32x4 we;
; #pragma unroll
;     for (int i = 0; i < 4; ++i) { const float W = __expf(-c[i]), iW = __expf(c[i]), Wp = __expf(d[i] - c[i]); o1[i] = RWKV ? kk[i] * Wp : 0.f; o2[i] = RWKV ? nb[i] * iW : 0.f; o3[i] = k[i] * iW; o4[i] = r[i] * W; we[i] = W; }
;     u32x2 w;
;     w.x = cvt2(o1[0], o1[1]); w.y = cvt2(o1[2], o1[3]); *(LAS u32x2*)(buf + SB_XA + sl * 144 + col * 2) = w;
;     w.x = cvt2(o4[0], o4[1]); w.y = cvt2(o4[2], o4[3]); *(LAS u32x2*)(buf + SB_XA + (16 + sl) * 144 + col * 2) = w;
;     w.x = cvt2(o2[0], o2[1]); w.y = cvt2(o2[2], o2[3]); *(LAS u32x2*)(buf + SB_XB + sl * 144 + col * 2) = w;
;     w.x = cvt2(o3[0], o3[1]); w.y = cvt2(o3[2], o3[3]); *(LAS u32x2*)(buf + SB_XB + (16 + sl) * 144 + col * 2) = w;
; #pragma unroll
;     for (int i = 0; i < 4; ++i) {
;         *(LAS unsigned short*)(buf + SB_XBT + (col + i) * 80 + sl * 2) = (unsigned short)(cvt2(o2[i], 0.f) & 0xffffu);
;         *(LAS unsigned short*)(buf + SB_XBT + (col + i) * 80 + (16 + sl) * 2) = (unsigned short)(cvt2(o3[i], 0.f) & 0xffffu);
;         *(LAS unsigned short*)(buf + SB_VT + (col + i) * 48 + sl * 2) = (unsigned short)(cvt2(v[i], 0.f) & 0xffffu); }
; template <bool RWKV> __device__ __forceinline__ void scan_item(LAS unsigned char* lds, const ScanSrc& S, int wid, int lane) {
;     ...
;             if (c + 3 < NCH) scan_load_finish<RWKV>(lds + ((b0 + 3) & 3) * SC_BUF, L, lt);
;             if (c + 4 < NCH) scan_load_issue<RWKV>(L, S, c + 4, lt); }
.Lrw_ld_s3:
	s_cmpk_gt_u32 s69, 0xf8
	s_cbranch_scc1 .Lrw_ld_s3_tail
	s_waitcnt vmcnt(18)
	v_lshlrev_b32_e32 v32, 16, v12
	v_and_b32_e32 v33, 0xffff0000, v12
	v_lshlrev_b32_e32 v34, 16, v13
	v_and_b32_e32 v35, 0xffff0000, v13
	v_mul_f32_e32 v52, 0x3fb8aa3b, v32
	v_mul_f32_e32 v53, 0x3fb8aa3b, v33
	v_mul_f32_e32 v54, 0x3fb8aa3b, v34
	v_mul_f32_e32 v55, 0x3fb8aa3b, v35
	v_add_f32_dpp v52, v52, v52 row_shr:4 row_mask:0xf bank_mask:0xf
	v_add_f32_dpp v53, v53, v53 row_shr:4 row_mask:0xf bank_mask:0xf
	v_add_f32_dpp v54, v54, v54 row_shr:4 row_mask:0xf bank_mask:0xf
	v_add_f32_dpp v55, v55, v55 row_shr:4 row_mask:0xf bank_mask:0xf
	v_add_f32_dpp v52, v52, v52 row_shr:8 row_mask:0xf bank_mask:0xf
	v_add_f32_dpp v53, v53, v53 row_shr:8 row_mask:0xf bank_mask:0xf
	v_add_f32_dpp v54, v54, v54 row_shr:8 row_mask:0xf bank_mask:0xf
	v_add_f32_dpp v55, v55, v55 row_shr:8 row_mask:0xf bank_mask:0xf
	ds_bpermute_b32 v60, v251, v52
	ds_bpermute_b32 v61, v251, v53
	ds_bpermute_b32 v62, v251, v54
	ds_bpermute_b32 v63, v251, v55
	ds_write_b16 v190, v18 offset:14336
	ds_write_b16_d16_hi v190, v18 offset:14384
	ds_write_b16 v190, v19 offset:14432
	ds_write_b16_d16_hi v190, v19 offset:14480
	v_lshlrev_b32_e32 v36, 16, v14
	v_and_b32_e32 v37, 0xffff0000, v14
	v_lshlrev_b32_e32 v38, 16, v15
	v_and_b32_e32 v39, 0xffff0000, v15
	v_lshlrev_b32_e32 v40, 16, v16
	v_and_b32_e32 v41, 0xffff0000, v16
	v_lshlrev_b32_e32 v42, 16, v17
	v_and_b32_e32 v43, 0xffff0000, v17
	v_lshlrev_b32_e32 v44, 16, v20
	v_and_b32_e32 v45, 0xffff0000, v20
	v_lshlrev_b32_e32 v46, 16, v21
	v_and_b32_e32 v47, 0xffff0000, v21
	v_lshlrev_b32_e32 v48, 16, v22
	v_and_b32_e32 v49, 0xffff0000, v22
	v_lshlrev_b32_e32 v50, 16, v23
	v_and_b32_e32 v51, 0xffff0000, v23
	s_waitcnt lgkmcnt(4)
	v_fmac_f32_e32 v52, v60, v253
	v_fmac_f32_e32 v53, v61, v253
	v_fmac_f32_e32 v54, v62, v253
	v_fmac_f32_e32 v55, v63, v253
	ds_bpermute_b32 v60, v252, v52
	ds_bpermute_b32 v61, v252, v53
	ds_bpermute_b32 v62, v252, v54
	ds_bpermute_b32 v63, v252, v55
	global_load_dwordx2 v[12:13], v[234:235], off
	global_load_dwordx2 v[14:15], v[236:237], off
	global_load_dwordx2 v[16:17], v[238:239], off
	global_load_dwordx2 v[18:19], v[240:241], off
	global_load_dwordx2 v[20:21], v[242:243], off
	global_load_dwordx2 v[22:23], v[246:247], off
	v_lshl_add_u64 v[234:235], v[234:235], 0, s[98:99]
	v_lshl_add_u64 v[236:237], v[236:237], 0, s[100:101]
	v_lshl_add_u64 v[238:239], v[238:239], 0, s[100:101]
	v_lshl_add_u64 v[240:241], v[240:241], 0, s[100:101]
	v_lshl_add_u64 v[242:243], v[242:243], 0, s[98:99]
	v_lshl_add_u64 v[246:247], v[246:247], 0, s[98:99]
	s_waitcnt lgkmcnt(0)
	v_fmac_f32_e32 v52, v60, v245
	v_fmac_f32_e32 v53, v61, v245
	v_fmac_f32_e32 v54, v62, v245
	v_fmac_f32_e32 v55, v63, v245
	s_branch .Lrw_ldfin
.Lrw_ld_s3_tail:
	s_waitcnt vmcnt(0)
	v_lshlrev_b32_e32 v32, 16, v12
	v_and_b32_e32 v33, 0xffff0000, v12
	v_lshlrev_b32_e32 v34, 16, v13
	v_and_b32_e32 v35, 0xffff0000, v13
	v_mul_f32_e32 v52, 0x3fb8aa3b, v32
	v_mul_f32_e32 v53, 0x3fb8aa3b, v33
	v_mul_f32_e32 v54, 0x3fb8aa3b, v34
	v_mul_f32_e32 v55, 0x3fb8aa3b, v35
	v_add_f32_dpp v52, v52, v52 row_shr:4 row_mask:0xf bank_mask:0xf
	v_add_f32_dpp v53, v53, v53 row_shr:4 row_mask:0xf bank_mask:0xf
	v_add_f32_dpp v54, v54, v54 row_shr:4 row_mask:0xf bank_mask:0xf
	v_add_f32_dpp v55, v55, v55 row_shr:4 row_mask:0xf bank_mask:0xf
	v_add_f32_dpp v52, v52, v52 row_shr:8 row_mask:0xf bank_mask:0xf
	v_add_f32_dpp v53, v53, v53 row_shr:8 row_mask:0xf bank_mask:0xf
	v_add_f32_dpp v54, v54, v54 row_shr:8 row_mask:0xf bank_mask:0xf
	v_add_f32_dpp v55, v55, v55 row_shr:8 row_mask:0xf bank_mask:0xf
	ds_bpermute_b32 v60, v251, v52
	ds_bpermute_b32 v61, v251, v53
	ds_bpermute_b32 v62, v251, v54
	ds_bpermute_b32 v63, v251, v55
	ds_write_b16 v190, v18 offset:14336
	ds_write_b16_d16_hi v190, v18 offset:14384
	ds_write_b16 v190, v19 offset:14432
	ds_write_b16_d16_hi v190, v19 offset:14480
	v_lshlrev_b32_e32 v36, 16, v14
	v_and_b32_e32 v37, 0xffff0000, v14
	v_lshlrev_b32_e32 v38, 16, v15
	v_and_b32_e32 v39, 0xffff0000, v15
	v_lshlrev_b32_e32 v40, 16, v16
	v_and_b32_e32 v41, 0xffff0000, v16
	v_lshlrev_b32_e32 v42, 16, v17
	v_and_b32_e32 v43, 0xffff0000, v17
	v_lshlrev_b32_e32 v44, 16, v20
	v_and_b32_e32 v45, 0xffff0000, v20
	v_lshlrev_b32_e32 v46, 16, v21
	v_and_b32_e32 v47, 0xffff0000, v21
	v_lshlrev_b32_e32 v48, 16, v22
	v_and_b32_e32 v49, 0xffff0000, v22
	v_lshlrev_b32_e32 v50, 16, v23
	v_and_b32_e32 v51, 0xffff0000, v23
	s_waitcnt lgkmcnt(4)
	v_fmac_f32_e32 v52, v60, v253
	v_fmac_f32_e32 v53, v61, v253
	v_fmac_f32_e32 v54, v62, v253
	v_fmac_f32_e32 v55, v63, v253
	ds_bpermute_b32 v60, v252, v52
	ds_bpermute_b32 v61, v252, v53
	ds_bpermute_b32 v62, v252, v54
	ds_bpermute_b32 v63, v252, v55
	s_waitcnt lgkmcnt(0)
	v_fmac_f32_e32 v52, v60, v245
	v_fmac_f32_e32 v53, v61, v245
	v_fmac_f32_e32 v54, v62, v245
	v_fmac_f32_e32 v55, v63, v245
